# P1: two of eight epilogue row-blocks deferred into the next unit's first K-iteration
# baseline (speedup 1.0000x reference)
; #define PG8_STAGE(bufoff, gbase, voff) do { _Pragma("unroll") for (int _i = 0; _i < 2; ++_i) \
;         __builtin_amdgcn_global_load_lds((const unsigned*)((const char*)(gbase) + (voff)[_i]), (PG8_LAS unsigned*)(lds + (bufoff) + ldsw + _i * 8192), 16, 0, 0); } while (0)
; #define PG8_BAR __builtin_amdgcn_s_barrier()
; template <class Epi, class Sched, bool ALIGN_EPI = false, bool SP2 = false>
; __device__ __forceinline__ void gemm_phase(PG8_LAS unsigned char* lds, const Gemm g, const Sched& S, const Epi& E) {
;     ...
;         const bool has_next = S.next(ui + 1, nxt);
;         const char* nA = has_next ? (const char*)g.A + (size_t)nxt.pm * tstep : cA; const char* nB = has_next ? (const char*)g.Bt + (size_t)nxt.pn * tstep : cB;
;         for (int t = 0; t < nt; t += 2) {
;             const bool last = (t == nt - 2);
;             const char* a1 = cA + (size_t)(t + 1) * kstep;
;             const char* a2 = last ? nA : cA + (size_t)(t + 2) * kstep; const char* b2 = last ? nB : cB + (size_t)(t + 2) * kstep;
;             const char* a3 = a2 + kstep; const char* b3 = b2 + kstep;
;             if (last && has_next) S.a_ready(nxt);
;             if constexpr (SP2) {
;             PG8_LDB(B0, 0, 0); PG8_LDB(B1, 0, 1); PG8_SCHED; PG8_LDA(At, 0, 0); PG8_STAGE(PG8_SA(1, 1), a1 + hstep, voffA);
;             PG8_WAIT_V(8); PG8_WAIT_L(0); PG8_BAR; PG8_MMA(0, 0, At, B0); PG8_MMA(0, 1, At, B1); PG8_BAR; PG8_SCHED;
;     __device__ __forceinline__ void operator()(const f32x4 (&acc)[2][2][4][2], const pg8::Unit& u, int wr, int wc, int fr, int fq) const {
;         const int row0 = u.pm * 256 + wr * 64 + fr, col = u.pn * 128 + wc * 32 + 8 * fq;
; #pragma unroll
;         for (int ai = 0; ai < 2; ++ai)
; #pragma unroll
;             for (int m = 0; m < 4; ++m) {
;                 const int row = row0 + ai * 128 + m * 16;
;                 const float rs = sumsq ? rsqrtf(sumsq[row] * (1.f / 1024.f) + EPS) : 1.f;
;                 float o[8];
; #pragma unroll
;                 for (int n = 0; n < 2; ++n)
; #pragma unroll
;                     for (int e = 0; e < 4; ++e) { const float g = acc[ai][0][m][n][e] * rs, up = acc[ai][1][m][n][e] * rs; o[4 * n + e] = silu_f(g) * up; }
;                 u32x4 w; w.x = pk2(o[0], o[1]); w.y = pk2(o[2], o[3]); w.z = pk2(o[4], o[5]); w.w = pk2(o[6], o[7]);
;                 *(u32x4*)(H + (size_t)row * DFF + col) = w;
.LBB0_191:
	s_ashr_i32 s15, s14, 31
	s_lshl_b64 s[16:17], s[14:15], 19
	v_readlane_b32 s18, v235, 31
	v_readlane_b32 s19, v235, 32
	s_add_u32 s16, s18, s16
	s_addc_u32 s17, s19, s17
	s_and_b64 s[18:19], s[0:1], exec
	s_cselect_b32 s15, s17, s23
	s_cselect_b32 s50, s16, s22
	s_ashr_i32 s9, s8, 31
	s_lshl_b64 s[18:19], s[8:9], 19
	s_add_u32 s18, s33, s18
	s_addc_u32 s19, s34, s19
	s_and_b64 s[30:31], s[0:1], exec
	s_cselect_b32 s9, s19, s25
	s_cselect_b32 s51, s18, s24
	s_add_u32 s22, s22, 0x40080
	s_addc_u32 s23, s23, 0
	s_add_u32 s52, s24, 0x100
	s_addc_u32 s53, s25, 0
	s_mov_b32 s54, -2
	s_cmp_eq_u32 s98, 0
	s_cbranch_scc1 .Lp1_plain
	ds_read_b128 v[150:153], v147
	ds_read_b128 v[154:157], v147 offset:1024
	ds_read_b128 v[158:161], v147 offset:2048
	ds_read_b128 v[162:165], v147 offset:3072
	ds_read_b128 v[166:169], v148
	ds_read_b128 v[170:173], v148 offset:1024
	ds_read_b128 v[174:177], v148 offset:2048
	ds_read_b128 v[178:181], v148 offset:3072
	s_add_u32 s24, s22, 0xfffc0080
	s_addc_u32 s25, s23, -1
	s_cmp_eq_u32 s54, 12
	s_cselect_b32 s31, s15, s25
	s_cselect_b32 s30, s50, s24
	s_cselect_b32 s25, s9, s53
	s_cselect_b32 s24, s51, s52
	v_lshl_add_u64 v[186:187], s[22:23], 0, v[136:137]
	s_add_i32 m0, s21, 0xc000
	ds_read_b128 v[182:185], v149
	ds_read_b128 v[192:195], v149 offset:1024
	ds_read_b128 v[196:199], v149 offset:2048
	ds_read_b128 v[200:203], v149 offset:3072
	ds_read_b128 v[204:207], v149 offset:4096
	ds_read_b128 v[208:211], v149 offset:5120
	ds_read_b128 v[212:215], v149 offset:6144
	ds_read_b128 v[216:219], v149 offset:7168
	global_load_lds_dwordx4 v[186:187], off
	v_lshl_add_u64 v[186:187], s[22:23], 0, v[138:139]
	s_add_i32 m0, s21, 0xe000
	s_nop 0
	global_load_lds_dwordx4 v[186:187], off
	s_nop 1
	v_add_f32_e32 v32, 1.0, v38
	v_rcp_f32_e32 v32, v32
	v_add_f32_e32 v33, 1.0, v39
	v_rcp_f32_e32 v33, v33
	v_add_u32_e32 v34, 0xa0, v228
	v_mul_f32_e32 v28, v28, v32
	v_mul_f32_e32 v20, v28, v20
	v_mul_f32_e32 v28, v29, v33
	v_mul_f32_e32 v29, 0xbfb8aa3b, v30
	v_exp_f32_e32 v29, v29
	v_mul_f32_e32 v32, 0xbfb8aa3b, v31
	v_exp_f32_e32 v32, v32
	v_mul_f32_e32 v21, v28, v21
	v_add_f32_e32 v28, 1.0, v29
	v_rcp_f32_e32 v28, v28
	v_add_f32_e32 v29, 1.0, v32
	v_mul_f32_e32 v32, 0xbfb8aa3b, v24
	v_rcp_f32_e32 v29, v29
	v_exp_f32_e32 v32, v32
	v_mul_f32_e32 v28, v30, v28
	v_mul_f32_e32 v22, v28, v22
	v_mul_f32_e32 v28, v31, v29
	v_add_f32_e32 v29, 1.0, v32
	v_rcp_f32_e32 v29, v29
	v_mul_f32_e32 v30, 0xbfb8aa3b, v25
	v_exp_f32_e32 v30, v30
	v_mul_f32_e32 v23, v28, v23
	v_mul_f32_e32 v24, v24, v29
	v_mul_f32_e32 v24, v24, v16
	v_add_f32_e32 v16, 1.0, v30
	v_mul_f32_e32 v28, 0xbfb8aa3b, v26
	v_rcp_f32_e32 v16, v16
	v_exp_f32_e32 v28, v28
	v_mul_f32_e32 v29, 0xbfb8aa3b, v27
	v_exp_f32_e32 v29, v29
	v_mul_f32_e32 v16, v25, v16
	v_add_f32_e32 v25, 1.0, v28
	v_rcp_f32_e32 v25, v25
	v_add_f32_e32 v28, 1.0, v29
	v_rcp_f32_e32 v28, v28
	v_mul_f32_e32 v29, v16, v17
	v_mul_f32_e32 v16, v26, v25
	v_mul_f32_e32 v25, v16, v18
	v_mul_f32_e32 v16, v27, v28
	v_mul_f32_e32 v19, v16, v19
	v_cvt_pk_bf16_f32 v16, v20, v21
	v_cvt_pk_bf16_f32 v17, v22, v23
	v_mul_f32_e32 v22, 0xbfb8aa3b, v12
	v_exp_f32_e32 v22, v22
	v_mul_f32_e32 v23, 0xbfb8aa3b, v13
	v_exp_f32_e32 v23, v23
	v_mad_i64_i32 v[20:21], s[100:101], v34, s48, v[112:113]
	v_lshl_add_u64 v[20:21], v[20:21], 0, v[114:115]
	v_cvt_pk_bf16_f32 v18, v24, v29
	v_cvt_pk_bf16_f32 v19, v25, v19
	global_store_dwordx4 v[20:21], v[16:19], off
	s_nop 1
	v_add_f32_e32 v16, 1.0, v22
	v_rcp_f32_e32 v16, v16
	v_add_f32_e32 v17, 1.0, v23
	v_rcp_f32_e32 v17, v17
	v_add_u32_e32 v18, 0xb0, v228
	v_mul_f32_e32 v12, v12, v16
	v_mul_f32_e32 v4, v12, v4
	v_mul_f32_e32 v12, v13, v17
	v_mul_f32_e32 v13, 0xbfb8aa3b, v14
	v_exp_f32_e32 v13, v13
	v_mul_f32_e32 v16, 0xbfb8aa3b, v15
	v_exp_f32_e32 v16, v16
	v_mul_f32_e32 v5, v12, v5
	v_add_f32_e32 v12, 1.0, v13
	v_rcp_f32_e32 v12, v12
	v_add_f32_e32 v13, 1.0, v16
	v_mul_f32_e32 v16, 0xbfb8aa3b, v8
	v_rcp_f32_e32 v13, v13
	v_exp_f32_e32 v16, v16
	v_mul_f32_e32 v12, v14, v12
	v_mul_f32_e32 v6, v12, v6
	v_mul_f32_e32 v12, v15, v13
	v_add_f32_e32 v13, 1.0, v16
	v_rcp_f32_e32 v13, v13
	v_mul_f32_e32 v14, 0xbfb8aa3b, v9
	v_exp_f32_e32 v14, v14
	v_mul_f32_e32 v7, v12, v7
	v_mul_f32_e32 v8, v8, v13
	v_mul_f32_e32 v8, v8, v0
	v_add_f32_e32 v0, 1.0, v14
	v_mul_f32_e32 v12, 0xbfb8aa3b, v10
	v_rcp_f32_e32 v0, v0
	v_exp_f32_e32 v12, v12
	v_mul_f32_e32 v13, 0xbfb8aa3b, v11
	v_exp_f32_e32 v13, v13
	v_mul_f32_e32 v0, v9, v0
	v_add_f32_e32 v9, 1.0, v12
	v_rcp_f32_e32 v9, v9
	v_add_f32_e32 v12, 1.0, v13
	v_rcp_f32_e32 v12, v12
	v_mul_f32_e32 v13, v0, v1
	v_mul_f32_e32 v0, v10, v9
	v_mul_f32_e32 v9, v0, v2
	v_mul_f32_e32 v0, v11, v12
	v_mul_f32_e32 v3, v0, v3
	v_cvt_pk_bf16_f32 v0, v4, v5
	v_mad_i64_i32 v[4:5], s[100:101], v18, s48, v[112:113]
	v_lshl_add_u64 v[4:5], v[4:5], 0, v[114:115]
	v_cvt_pk_bf16_f32 v1, v6, v7
	v_cvt_pk_bf16_f32 v2, v8, v13
	v_cvt_pk_bf16_f32 v3, v9, v3
	global_store_dwordx4 v[4:5], v[0:3], off
	s_waitcnt vmcnt(16)
	s_waitcnt lgkmcnt(0)
	s_barrier
; #define PG8_STAGE(bufoff, gbase, voff) do { _Pragma("unroll") for (int _i = 0; _i < 2; ++_i) \
;         __builtin_amdgcn_global_load_lds((const unsigned*)((const char*)(gbase) + (voff)[_i]), (PG8_LAS unsigned*)(lds + (bufoff) + ldsw + _i * 8192), 16, 0, 0); } while (0)
; #define PG8_LDA(dst, b, h) do { _Pragma("unroll") for (int m = 0; m < 4; ++m) _Pragma("unroll") for (int k = 0; k < 2; ++k) dst[m][k] = *(const PG8_LAS bf16x8*)(lds + PG8_SA(b, h) + aoff + m * 2048 + k * 1024); } while (0)
; #define PG8_LDB(dst, b, h) do { _Pragma("unroll") for (int n = 0; n < 2; ++n) _Pragma("unroll") for (int k = 0; k < 2; ++k) dst[n][k] = *(const PG8_LAS bf16x8*)(lds + PG8_SB(b, h) + boff + n * 2048 + k * 1024); } while (0)
; #define PG8_MMA(ai, bj, At, Bt) do { __builtin_amdgcn_s_setprio(1); _Pragma("unroll") for (int m = 0; m < 4; ++m) _Pragma("unroll") for (int n = 0; n < 2; ++n) _Pragma("unroll") for (int k = 0; k < 2; ++k) \
;         acc[ai][bj][m][n] = __builtin_amdgcn_mfma_f32_16x16x32_bf16(Bt[n][k], At[m][k], acc[ai][bj][m][n], 0, 0, 0); __builtin_amdgcn_s_setprio(0); } while (0)
; #define PG8_WAIT_V(n) asm volatile("s_waitcnt vmcnt(" #n ")" ::: "memory")
; #define PG8_WAIT_L(n) asm volatile("s_waitcnt lgkmcnt(" #n ")" ::: "memory")
; #define PG8_BAR __builtin_amdgcn_s_barrier()
; #define PG8_SCHED __builtin_amdgcn_sched_barrier(0)
; template <class Epi, class Sched, bool ALIGN_EPI = false, bool SP2 = false>
; __device__ __forceinline__ void gemm_phase(PG8_LAS unsigned char* lds, const Gemm g, const Sched& S, const Epi& E) {
;     ...
;             PG8_LDB(B0, 0, 0); PG8_LDB(B1, 0, 1); PG8_SCHED; PG8_LDA(At, 0, 0); PG8_STAGE(PG8_SA(1, 1), a1 + hstep, voffA);
;             PG8_WAIT_V(8); PG8_WAIT_L(0); PG8_BAR; PG8_MMA(0, 0, At, B0); PG8_MMA(0, 1, At, B1); PG8_BAR; PG8_SCHED;
;             PG8_LDA(At, 0, 1); PG8_STAGE(PG8_SB(0, 0), b2, voffB); PG8_STAGE(PG8_SB(0, 1), b2 + hstep, voffB); PG8_STAGE(PG8_SA(0, 0), a2, voffA);
;             PG8_WAIT_V(8); PG8_WAIT_L(0); PG8_BAR; PG8_MMA(1, 0, At, B0); PG8_MMA(1, 1, At, B1); PG8_BAR; PG8_SCHED;
	s_setprio 1
	v_mfma_f32_16x16x32_bf16 v[124:127], v[150:153], v[182:185], 0
	v_mfma_f32_16x16x32_bf16 v[120:123], v[158:161], v[182:185], 0
	v_mfma_f32_16x16x32_bf16 v[108:111], v[150:153], v[196:199], 0
	v_mfma_f32_16x16x32_bf16 v[104:107], v[158:161], v[196:199], 0
	v_mfma_f32_16x16x32_bf16 v[92:95], v[150:153], v[204:207], 0
	v_mfma_f32_16x16x32_bf16 v[88:91], v[158:161], v[204:207], 0
	v_mfma_f32_16x16x32_bf16 v[76:79], v[150:153], v[212:215], 0
	v_mfma_f32_16x16x32_bf16 v[72:75], v[158:161], v[212:215], 0
	v_mfma_f32_16x16x32_bf16 v[124:127], v[154:157], v[192:195], v[124:127]
	v_mfma_f32_16x16x32_bf16 v[120:123], v[162:165], v[192:195], v[120:123]
	v_mfma_f32_16x16x32_bf16 v[108:111], v[154:157], v[200:203], v[108:111]
	v_mfma_f32_16x16x32_bf16 v[104:107], v[162:165], v[200:203], v[104:107]
	v_mfma_f32_16x16x32_bf16 v[92:95], v[154:157], v[208:211], v[92:95]
	v_mfma_f32_16x16x32_bf16 v[88:91], v[162:165], v[208:211], v[88:91]
	v_mfma_f32_16x16x32_bf16 v[76:79], v[154:157], v[216:219], v[76:79]
	v_mfma_f32_16x16x32_bf16 v[72:75], v[162:165], v[216:219], v[72:75]
	v_mfma_f32_16x16x32_bf16 v[116:119], v[166:169], v[182:185], 0
	v_mfma_f32_16x16x32_bf16 v[112:115], v[174:177], v[182:185], 0
	v_mfma_f32_16x16x32_bf16 v[100:103], v[166:169], v[196:199], 0
	v_mfma_f32_16x16x32_bf16 v[96:99], v[174:177], v[196:199], 0
	v_mfma_f32_16x16x32_bf16 v[84:87], v[166:169], v[204:207], 0
	v_mfma_f32_16x16x32_bf16 v[80:83], v[174:177], v[204:207], 0
	v_mfma_f32_16x16x32_bf16 v[68:71], v[166:169], v[212:215], 0
	v_mfma_f32_16x16x32_bf16 v[64:67], v[174:177], v[212:215], 0
	v_mfma_f32_16x16x32_bf16 v[116:119], v[170:173], v[192:195], v[116:119]
	v_mfma_f32_16x16x32_bf16 v[112:115], v[178:181], v[192:195], v[112:115]
	v_mfma_f32_16x16x32_bf16 v[100:103], v[170:173], v[200:203], v[100:103]
	v_mfma_f32_16x16x32_bf16 v[96:99], v[178:181], v[200:203], v[96:99]
	v_mfma_f32_16x16x32_bf16 v[84:87], v[170:173], v[208:211], v[84:87]
	v_mfma_f32_16x16x32_bf16 v[80:83], v[178:181], v[208:211], v[80:83]
	v_mfma_f32_16x16x32_bf16 v[68:71], v[170:173], v[216:219], v[68:71]
	v_mfma_f32_16x16x32_bf16 v[64:67], v[178:181], v[216:219], v[64:67]
	s_setprio 0
	s_barrier
	s_add_i32 s55, s46, s35
	v_lshl_add_u64 v[186:187], s[24:25], 0, v[132:133]
	s_mov_b32 m0, s55
	ds_read_b128 v[182:185], v149 offset:16384
	ds_read_b128 v[192:195], v149 offset:17408
	ds_read_b128 v[196:199], v149 offset:18432
	ds_read_b128 v[200:203], v149 offset:19456
	ds_read_b128 v[204:207], v149 offset:20480
	ds_read_b128 v[208:211], v149 offset:21504
	ds_read_b128 v[212:215], v149 offset:22528
	ds_read_b128 v[216:219], v149 offset:23552
	global_load_lds_dwordx4 v[186:187], off
	s_add_i32 m0, s55, 0x2000
	s_add_u32 s56, s24, 0x40000
	v_lshl_add_u64 v[220:221], s[24:25], 0, v[128:129]
	s_addc_u32 s57, s25, 0
	s_add_i32 s55, s47, s35
	global_load_lds_dwordx4 v[220:221], off
	v_lshl_add_u64 v[222:223], s[56:57], 0, v[132:133]
	s_mov_b32 m0, s55
	v_lshl_add_u64 v[224:225], s[30:31], 0, v[130:131]
	global_load_lds_dwordx4 v[222:223], off
	v_lshl_add_u64 v[222:223], s[56:57], 0, v[128:129]
	s_add_i32 m0, s55, 0x2000
	s_nop 0
	global_load_lds_dwordx4 v[222:223], off
	v_lshl_add_u64 v[222:223], s[30:31], 0, v[134:135]
	s_mov_b32 m0, s21
	s_nop 0
	global_load_lds_dwordx4 v[222:223], off
	s_mov_b32 m0, s38
	s_nop 0
	global_load_lds_dwordx4 v[224:225], off
	s_waitcnt vmcnt(16)
	s_waitcnt lgkmcnt(0)
	s_barrier
	s_setprio 1
	v_mfma_f32_16x16x32_bf16 v[60:63], v[150:153], v[182:185], 0
	v_mfma_f32_16x16x32_bf16 v[56:59], v[158:161], v[182:185], 0
	v_mfma_f32_16x16x32_bf16 v[44:47], v[150:153], v[196:199], 0
	v_mfma_f32_16x16x32_bf16 v[40:43], v[158:161], v[196:199], 0
	v_mfma_f32_16x16x32_bf16 v[28:31], v[150:153], v[204:207], 0
	v_mfma_f32_16x16x32_bf16 v[24:27], v[158:161], v[204:207], 0
	v_mfma_f32_16x16x32_bf16 v[12:15], v[150:153], v[212:215], 0
	v_mfma_f32_16x16x32_bf16 v[8:11], v[158:161], v[212:215], 0
	v_mfma_f32_16x16x32_bf16 v[60:63], v[154:157], v[192:195], v[60:63]
	v_mfma_f32_16x16x32_bf16 v[56:59], v[162:165], v[192:195], v[56:59]
	v_mfma_f32_16x16x32_bf16 v[44:47], v[154:157], v[200:203], v[44:47]
	v_mfma_f32_16x16x32_bf16 v[40:43], v[162:165], v[200:203], v[40:43]
	v_mfma_f32_16x16x32_bf16 v[28:31], v[154:157], v[208:211], v[28:31]
	v_mfma_f32_16x16x32_bf16 v[24:27], v[162:165], v[208:211], v[24:27]
	v_mfma_f32_16x16x32_bf16 v[12:15], v[154:157], v[216:219], v[12:15]
	v_mfma_f32_16x16x32_bf16 v[8:11], v[162:165], v[216:219], v[8:11]
	v_mfma_f32_16x16x32_bf16 v[52:55], v[166:169], v[182:185], 0
	v_mfma_f32_16x16x32_bf16 v[48:51], v[174:177], v[182:185], 0
	v_mfma_f32_16x16x32_bf16 v[36:39], v[166:169], v[196:199], 0
	v_mfma_f32_16x16x32_bf16 v[32:35], v[174:177], v[196:199], 0
	v_mfma_f32_16x16x32_bf16 v[20:23], v[166:169], v[204:207], 0
	v_mfma_f32_16x16x32_bf16 v[16:19], v[174:177], v[204:207], 0
	v_mfma_f32_16x16x32_bf16 v[4:7], v[166:169], v[212:215], 0
	v_mfma_f32_16x16x32_bf16 v[0:3], v[174:177], v[212:215], 0
	v_mfma_f32_16x16x32_bf16 v[52:55], v[170:173], v[192:195], v[52:55]
	v_mfma_f32_16x16x32_bf16 v[48:51], v[178:181], v[192:195], v[48:51]
	v_mfma_f32_16x16x32_bf16 v[36:39], v[170:173], v[200:203], v[36:39]
	v_mfma_f32_16x16x32_bf16 v[32:35], v[178:181], v[200:203], v[32:35]
	v_mfma_f32_16x16x32_bf16 v[20:23], v[170:173], v[208:211], v[20:23]
	v_mfma_f32_16x16x32_bf16 v[16:19], v[178:181], v[208:211], v[16:19]
	v_mfma_f32_16x16x32_bf16 v[4:7], v[170:173], v[216:219], v[4:7]
	v_mfma_f32_16x16x32_bf16 v[0:3], v[178:181], v[216:219], v[0:3]
	s_setprio 0
	s_barrier
; #define PG8_STAGE(bufoff, gbase, voff) do { _Pragma("unroll") for (int _i = 0; _i < 2; ++_i) \
;         __builtin_amdgcn_global_load_lds((const unsigned*)((const char*)(gbase) + (voff)[_i]), (PG8_LAS unsigned*)(lds + (bufoff) + ldsw + _i * 8192), 16, 0, 0); } while (0)
; #define PG8_LDA(dst, b, h) do { _Pragma("unroll") for (int m = 0; m < 4; ++m) _Pragma("unroll") for (int k = 0; k < 2; ++k) dst[m][k] = *(const PG8_LAS bf16x8*)(lds + PG8_SA(b, h) + aoff + m * 2048 + k * 1024); } while (0)
; #define PG8_LDB(dst, b, h) do { _Pragma("unroll") for (int n = 0; n < 2; ++n) _Pragma("unroll") for (int k = 0; k < 2; ++k) dst[n][k] = *(const PG8_LAS bf16x8*)(lds + PG8_SB(b, h) + boff + n * 2048 + k * 1024); } while (0)
; #define PG8_MMA(ai, bj, At, Bt) do { __builtin_amdgcn_s_setprio(1); _Pragma("unroll") for (int m = 0; m < 4; ++m) _Pragma("unroll") for (int n = 0; n < 2; ++n) _Pragma("unroll") for (int k = 0; k < 2; ++k) \
;         acc[ai][bj][m][n] = __builtin_amdgcn_mfma_f32_16x16x32_bf16(Bt[n][k], At[m][k], acc[ai][bj][m][n], 0, 0, 0); __builtin_amdgcn_s_setprio(0); } while (0)
; #define PG8_WAIT_V(n) asm volatile("s_waitcnt vmcnt(" #n ")" ::: "memory")
; #define PG8_WAIT_L(n) asm volatile("s_waitcnt lgkmcnt(" #n ")" ::: "memory")
; #define PG8_BAR __builtin_amdgcn_s_barrier()
; #define PG8_SCHED __builtin_amdgcn_sched_barrier(0)
; template <class Epi, class Sched, bool ALIGN_EPI = false, bool SP2 = false>
; __device__ __forceinline__ void gemm_phase(PG8_LAS unsigned char* lds, const Gemm g, const Sched& S, const Epi& E) {
;     ...
;             PG8_LDB(B0, 1, 0); PG8_LDB(B1, 1, 1); PG8_SCHED; PG8_LDA(At, 1, 0); PG8_STAGE(PG8_SA(0, 1), a2 + hstep, voffA);
;             PG8_WAIT_V(8); PG8_WAIT_L(0); PG8_BAR; PG8_MMA(0, 0, At, B0); PG8_MMA(0, 1, At, B1); PG8_BAR; PG8_SCHED;
;             PG8_LDA(At, 1, 1); PG8_STAGE(PG8_SB(1, 0), b3, voffB); PG8_STAGE(PG8_SB(1, 1), b3 + hstep, voffB); PG8_STAGE(PG8_SA(1, 0), a3, voffA);
;             PG8_WAIT_V(8); PG8_WAIT_L(0); PG8_BAR; PG8_MMA(1, 0, At, B0); PG8_MMA(1, 1, At, B1); PG8_BAR; PG8_SCHED;
	s_add_i32 s55, 0, 0x18000
	s_add_i32 s56, 0, 0x1c000
	v_add_u32_e32 v162, s55, v145
	v_add_u32_e32 v178, s56, v145
	ds_read_b128 v[150:153], v162
	ds_read_b128 v[154:157], v162 offset:1024
	ds_read_b128 v[158:161], v162 offset:2048
	ds_read_b128 v[162:165], v162 offset:3072
	ds_read_b128 v[166:169], v178
	ds_read_b128 v[170:173], v178 offset:1024
	ds_read_b128 v[174:177], v178 offset:2048
	ds_read_b128 v[178:181], v178 offset:3072
	s_add_u32 s30, s30, 0x40000
	s_addc_u32 s31, s31, 0
	s_mov_b32 m0, s39
	v_lshl_add_u64 v[226:227], s[30:31], 0, v[134:135]
	ds_read_b128 v[182:185], v149 offset:32768
	ds_read_b128 v[192:195], v149 offset:33792
	ds_read_b128 v[196:199], v149 offset:34816
	ds_read_b128 v[200:203], v149 offset:35840
	ds_read_b128 v[204:207], v149 offset:36864
	ds_read_b128 v[208:211], v149 offset:37888
	ds_read_b128 v[212:215], v149 offset:38912
	ds_read_b128 v[216:219], v149 offset:39936
	global_load_lds_dwordx4 v[226:227], off
	v_lshl_add_u64 v[226:227], s[30:31], 0, v[130:131]
	s_mov_b32 m0, s40
	s_nop 0
	global_load_lds_dwordx4 v[226:227], off
	s_waitcnt vmcnt(8)
	s_waitcnt lgkmcnt(0)
	s_barrier
	s_setprio 1
	v_mfma_f32_16x16x32_bf16 v[124:127], v[150:153], v[182:185], v[124:127]
	v_mfma_f32_16x16x32_bf16 v[120:123], v[158:161], v[182:185], v[120:123]
	v_mfma_f32_16x16x32_bf16 v[108:111], v[150:153], v[196:199], v[108:111]
	v_mfma_f32_16x16x32_bf16 v[104:107], v[158:161], v[196:199], v[104:107]
	v_mfma_f32_16x16x32_bf16 v[92:95], v[150:153], v[204:207], v[92:95]
	v_mfma_f32_16x16x32_bf16 v[88:91], v[158:161], v[204:207], v[88:91]
	v_mfma_f32_16x16x32_bf16 v[76:79], v[150:153], v[212:215], v[76:79]
	v_mfma_f32_16x16x32_bf16 v[72:75], v[158:161], v[212:215], v[72:75]
	v_mfma_f32_16x16x32_bf16 v[124:127], v[154:157], v[192:195], v[124:127]
	v_mfma_f32_16x16x32_bf16 v[120:123], v[162:165], v[192:195], v[120:123]
	v_mfma_f32_16x16x32_bf16 v[108:111], v[154:157], v[200:203], v[108:111]
	v_mfma_f32_16x16x32_bf16 v[104:107], v[162:165], v[200:203], v[104:107]
	v_mfma_f32_16x16x32_bf16 v[92:95], v[154:157], v[208:211], v[92:95]
	v_mfma_f32_16x16x32_bf16 v[88:91], v[162:165], v[208:211], v[88:91]
	v_mfma_f32_16x16x32_bf16 v[76:79], v[154:157], v[216:219], v[76:79]
	v_mfma_f32_16x16x32_bf16 v[72:75], v[162:165], v[216:219], v[72:75]
	v_mfma_f32_16x16x32_bf16 v[116:119], v[166:169], v[182:185], v[116:119]
	v_mfma_f32_16x16x32_bf16 v[112:115], v[174:177], v[182:185], v[112:115]
	v_mfma_f32_16x16x32_bf16 v[100:103], v[166:169], v[196:199], v[100:103]
	v_mfma_f32_16x16x32_bf16 v[96:99], v[174:177], v[196:199], v[96:99]
	v_mfma_f32_16x16x32_bf16 v[84:87], v[166:169], v[204:207], v[84:87]
	v_mfma_f32_16x16x32_bf16 v[80:83], v[174:177], v[204:207], v[80:83]
	v_mfma_f32_16x16x32_bf16 v[68:71], v[166:169], v[212:215], v[68:71]
	v_mfma_f32_16x16x32_bf16 v[64:67], v[174:177], v[212:215], v[64:67]
	v_mfma_f32_16x16x32_bf16 v[116:119], v[170:173], v[192:195], v[116:119]
	v_mfma_f32_16x16x32_bf16 v[112:115], v[178:181], v[192:195], v[112:115]
	v_mfma_f32_16x16x32_bf16 v[100:103], v[170:173], v[200:203], v[100:103]
	v_mfma_f32_16x16x32_bf16 v[96:99], v[178:181], v[200:203], v[96:99]
	v_mfma_f32_16x16x32_bf16 v[84:87], v[170:173], v[208:211], v[84:87]
	v_mfma_f32_16x16x32_bf16 v[80:83], v[178:181], v[208:211], v[80:83]
	v_mfma_f32_16x16x32_bf16 v[68:71], v[170:173], v[216:219], v[68:71]
	v_mfma_f32_16x16x32_bf16 v[64:67], v[178:181], v[216:219], v[64:67]
	s_setprio 0
	s_barrier
	s_add_i32 s30, s55, s35
	v_lshl_add_u64 v[186:187], v[186:187], 0, s[4:5]
	s_mov_b32 m0, s30
	ds_read_b128 v[182:185], v149 offset:49152
	ds_read_b128 v[192:195], v149 offset:50176
	ds_read_b128 v[196:199], v149 offset:51200
	ds_read_b128 v[200:203], v149 offset:52224
	ds_read_b128 v[204:207], v149 offset:53248
	ds_read_b128 v[208:211], v149 offset:54272
	ds_read_b128 v[212:215], v149 offset:55296
	ds_read_b128 v[216:219], v149 offset:56320
	global_load_lds_dwordx4 v[186:187], off
	s_add_i32 m0, s30, 0x2000
	s_add_u32 s24, s24, 0x40080
	v_lshl_add_u64 v[186:187], v[220:221], 0, s[4:5]
	s_addc_u32 s25, s25, 0
	s_add_i32 s30, s56, s35
	global_load_lds_dwordx4 v[186:187], off
	v_lshl_add_u64 v[186:187], s[24:25], 0, v[132:133]
	s_mov_b32 m0, s30
	s_nop 0
	global_load_lds_dwordx4 v[186:187], off
	v_lshl_add_u64 v[186:187], s[24:25], 0, v[128:129]
	s_add_i32 m0, s30, 0x2000
	s_nop 0
	global_load_lds_dwordx4 v[186:187], off
	v_lshl_add_u64 v[186:187], v[222:223], 0, s[4:5]
	s_mov_b32 m0, s42
	s_nop 0
	global_load_lds_dwordx4 v[186:187], off
	v_lshl_add_u64 v[186:187], v[224:225], 0, s[4:5]
	s_mov_b32 m0, s43
	s_nop 0
	global_load_lds_dwordx4 v[186:187], off
	s_waitcnt vmcnt(8)
	s_waitcnt lgkmcnt(0)
	s_barrier
	s_setprio 1
	v_mfma_f32_16x16x32_bf16 v[60:63], v[150:153], v[182:185], v[60:63]
	v_mfma_f32_16x16x32_bf16 v[56:59], v[158:161], v[182:185], v[56:59]
	v_mfma_f32_16x16x32_bf16 v[44:47], v[150:153], v[196:199], v[44:47]
	v_mfma_f32_16x16x32_bf16 v[40:43], v[158:161], v[196:199], v[40:43]
	v_mfma_f32_16x16x32_bf16 v[28:31], v[150:153], v[204:207], v[28:31]
	v_mfma_f32_16x16x32_bf16 v[24:27], v[158:161], v[204:207], v[24:27]
	v_mfma_f32_16x16x32_bf16 v[12:15], v[150:153], v[212:215], v[12:15]
	v_mfma_f32_16x16x32_bf16 v[8:11], v[158:161], v[212:215], v[8:11]
	v_mfma_f32_16x16x32_bf16 v[60:63], v[154:157], v[192:195], v[60:63]
	v_mfma_f32_16x16x32_bf16 v[56:59], v[162:165], v[192:195], v[56:59]
	v_mfma_f32_16x16x32_bf16 v[44:47], v[154:157], v[200:203], v[44:47]
	v_mfma_f32_16x16x32_bf16 v[40:43], v[162:165], v[200:203], v[40:43]
	v_mfma_f32_16x16x32_bf16 v[28:31], v[154:157], v[208:211], v[28:31]
	v_mfma_f32_16x16x32_bf16 v[24:27], v[162:165], v[208:211], v[24:27]
	v_mfma_f32_16x16x32_bf16 v[12:15], v[154:157], v[216:219], v[12:15]
	v_mfma_f32_16x16x32_bf16 v[8:11], v[162:165], v[216:219], v[8:11]
	v_mfma_f32_16x16x32_bf16 v[52:55], v[166:169], v[182:185], v[52:55]
	v_mfma_f32_16x16x32_bf16 v[48:51], v[174:177], v[182:185], v[48:51]
	v_mfma_f32_16x16x32_bf16 v[36:39], v[166:169], v[196:199], v[36:39]
	v_mfma_f32_16x16x32_bf16 v[32:35], v[174:177], v[196:199], v[32:35]
	v_mfma_f32_16x16x32_bf16 v[20:23], v[166:169], v[204:207], v[20:23]
	v_mfma_f32_16x16x32_bf16 v[16:19], v[174:177], v[204:207], v[16:19]
	v_mfma_f32_16x16x32_bf16 v[4:7], v[166:169], v[212:215], v[4:7]
	v_mfma_f32_16x16x32_bf16 v[0:3], v[174:177], v[212:215], v[0:3]
	v_mfma_f32_16x16x32_bf16 v[52:55], v[170:173], v[192:195], v[52:55]
	v_mfma_f32_16x16x32_bf16 v[48:51], v[178:181], v[192:195], v[48:51]
	v_mfma_f32_16x16x32_bf16 v[36:39], v[170:173], v[200:203], v[36:39]
	v_mfma_f32_16x16x32_bf16 v[32:35], v[178:181], v[200:203], v[32:35]
	v_mfma_f32_16x16x32_bf16 v[20:23], v[170:173], v[208:211], v[20:23]
	v_mfma_f32_16x16x32_bf16 v[16:19], v[178:181], v[208:211], v[16:19]
	v_mfma_f32_16x16x32_bf16 v[4:7], v[170:173], v[216:219], v[4:7]
	v_mfma_f32_16x16x32_bf16 v[0:3], v[178:181], v[216:219], v[0:3]
	s_setprio 0
	s_barrier
	s_add_i32 s54, s54, 2
	s_add_u32 s22, s22, 0x100
	s_addc_u32 s23, s23, 0
	s_add_u32 s52, s52, 0x100
	s_addc_u32 s53, s53, 0
	s_branch .LBB0_192

; __device__ __forceinline__ unsigned pk2(float lo, float hi) { return pg8::cvt_pk_bf16(lo, hi); }
; __device__ __forceinline__ float silu_f(float x) { return x * sigmoid_f(x); }
; template <class Epi, class Sched, bool ALIGN_EPI = false, bool SP2 = false>
; __device__ __forceinline__ void gemm_phase(PG8_LAS unsigned char* lds, const Gemm g, const Sched& S, const Epi& E) {
;     ...
;         if constexpr (!Epi::AFTER_DRAIN) { E(acc, cur, wr, wc, fr, fq); S.done(cur); }
;         if (!has_next) break;
;     __device__ __forceinline__ void operator()(const f32x4 (&acc)[2][2][4][2], const pg8::Unit& u, int wr, int wc, int fr, int fq) const {
;         const int row0 = u.pm * 256 + wr * 64 + fr, col = u.pn * 128 + wc * 32 + 8 * fq;
; #pragma unroll
;         for (int ai = 0; ai < 2; ++ai)
; #pragma unroll
;             for (int m = 0; m < 4; ++m) {
;                 const int row = row0 + ai * 128 + m * 16;
;                 const float rs = sumsq ? rsqrtf(sumsq[row] * (1.f / 1024.f) + EPS) : 1.f;
;                 float o[8];
; #pragma unroll
;                 for (int n = 0; n < 2; ++n)
; #pragma unroll
;                     for (int e = 0; e < 4; ++e) { const float g = acc[ai][0][m][n][e] * rs, up = acc[ai][1][m][n][e] * rs; o[4 * n + e] = silu_f(g) * up; }
;                 u32x4 w; w.x = pk2(o[0], o[1]); w.y = pk2(o[2], o[3]); w.z = pk2(o[4], o[5]); w.w = pk2(o[6], o[7]);
;                 *(u32x4*)(H + (size_t)row * DFF + col) = w;
.LBB0_195:
	v_mul_f32_e32 v151, 0xbfb8aa3b, v124
	v_exp_f32_e32 v151, v151
	v_mul_f32_e32 v152, 0xbfb8aa3b, v125
	v_exp_f32_e32 v153, v152
	v_readlane_b32 s22, v235, 33
	v_add_f32_e32 v151, 1.0, v151
	v_rcp_f32_e32 v151, v151
	v_add_f32_e32 v153, 1.0, v153
	v_rcp_f32_e32 v154, v153
	v_lshl_or_b32 v152, s49, 7, v146
	v_mul_f32_e32 v124, v124, v151
	v_mul_f32_e32 v116, v124, v116
	v_mul_f32_e32 v124, v125, v154
	v_mul_f32_e32 v125, 0xbfb8aa3b, v126
	v_exp_f32_e32 v125, v125
	v_mul_f32_e32 v151, 0xbfb8aa3b, v127
	v_exp_f32_e32 v151, v151
	v_mul_f32_e32 v117, v124, v117
	v_add_f32_e32 v124, 1.0, v125
	v_rcp_f32_e32 v124, v124
	v_add_f32_e32 v125, 1.0, v151
	v_mul_f32_e32 v151, 0xbfb8aa3b, v120
	v_rcp_f32_e32 v125, v125
	v_exp_f32_e32 v151, v151
	v_mul_f32_e32 v124, v126, v124
	v_mul_f32_e32 v118, v124, v118
	v_mul_f32_e32 v124, v127, v125
	v_add_f32_e32 v125, 1.0, v151
	v_rcp_f32_e32 v125, v125
	v_mul_f32_e32 v126, 0xbfb8aa3b, v121
	v_exp_f32_e32 v126, v126
	v_mul_f32_e32 v119, v124, v119
	v_mul_f32_e32 v120, v120, v125
	v_mul_f32_e32 v112, v120, v112
	v_add_f32_e32 v120, 1.0, v126
	v_mul_f32_e32 v124, 0xbfb8aa3b, v122
	v_rcp_f32_e32 v120, v120
	v_exp_f32_e32 v124, v124
	v_mul_f32_e32 v125, 0xbfb8aa3b, v123
	v_exp_f32_e32 v125, v125
	v_mul_f32_e32 v120, v121, v120
	v_add_f32_e32 v121, 1.0, v124
	v_rcp_f32_e32 v121, v121
	v_add_f32_e32 v124, 1.0, v125
	v_rcp_f32_e32 v124, v124
	v_mul_f32_e32 v113, v120, v113
	v_mul_f32_e32 v120, v122, v121
	v_mul_f32_e32 v122, 0xbfb8aa3b, v108
	v_mul_f32_e32 v114, v120, v114
	v_mul_f32_e32 v120, v123, v124
	v_readlane_b32 s23, v235, 34
	v_exp_f32_e32 v122, v122
	v_mul_f32_e32 v123, 0xbfb8aa3b, v109
	v_lshl_add_u32 v150, s20, 8, v144
	v_mov_b32_e32 v228, v150
	v_ashrrev_i32_e32 v153, 31, v152
	v_mul_f32_e32 v115, v120, v115
	v_cvt_pk_bf16_f32 v116, v116, v117
	v_cvt_pk_bf16_f32 v117, v118, v119
	v_cvt_pk_bf16_f32 v118, v112, v113
	v_mov_b64_e32 v[112:113], s[22:23]
	v_exp_f32_e32 v123, v123
	v_cvt_pk_bf16_f32 v119, v114, v115
	v_mad_i64_i32 v[120:121], s[22:23], v150, s48, v[112:113]
	v_lshlrev_b64 v[114:115], 1, v[152:153]
	v_lshl_add_u64 v[120:121], v[120:121], 0, v[114:115]
	global_store_dwordx4 v[120:121], v[116:119], off
	s_andn2_b64 vcc, exec, s[0:1]
	s_mov_b64 s[0:1], -1
	v_add_f32_e32 v116, 1.0, v122
	v_rcp_f32_e32 v116, v116
	v_add_f32_e32 v117, 1.0, v123
	v_rcp_f32_e32 v117, v117
	v_or_b32_e32 v118, 16, v150
	v_mul_f32_e32 v108, v108, v116
	v_mul_f32_e32 v100, v108, v100
	v_mul_f32_e32 v108, v109, v117
	v_mul_f32_e32 v109, 0xbfb8aa3b, v110
	v_exp_f32_e32 v109, v109
	v_mul_f32_e32 v116, 0xbfb8aa3b, v111
	v_exp_f32_e32 v116, v116
	v_mul_f32_e32 v101, v108, v101
	v_add_f32_e32 v108, 1.0, v109
	v_rcp_f32_e32 v108, v108
	v_add_f32_e32 v109, 1.0, v116
	v_mul_f32_e32 v116, 0xbfb8aa3b, v104
	v_rcp_f32_e32 v109, v109
	v_exp_f32_e32 v116, v116
	v_mul_f32_e32 v108, v110, v108
	v_mul_f32_e32 v102, v108, v102
	v_mul_f32_e32 v108, v111, v109
	v_add_f32_e32 v109, 1.0, v116
	v_rcp_f32_e32 v109, v109
	v_mul_f32_e32 v110, 0xbfb8aa3b, v105
	v_exp_f32_e32 v110, v110
	v_mul_f32_e32 v103, v108, v103
	v_mul_f32_e32 v104, v104, v109
	v_mul_f32_e32 v104, v104, v96
	v_add_f32_e32 v96, 1.0, v110
	v_mul_f32_e32 v108, 0xbfb8aa3b, v106
	v_rcp_f32_e32 v96, v96
	v_exp_f32_e32 v108, v108
	v_mul_f32_e32 v109, 0xbfb8aa3b, v107
	v_exp_f32_e32 v109, v109
	v_mul_f32_e32 v96, v105, v96
	v_add_f32_e32 v105, 1.0, v108
	v_rcp_f32_e32 v105, v105
	v_add_f32_e32 v108, 1.0, v109
	v_rcp_f32_e32 v108, v108
	v_mul_f32_e32 v109, v96, v97
	v_mul_f32_e32 v96, v106, v105
	v_mul_f32_e32 v105, v96, v98
	v_mul_f32_e32 v96, v107, v108
	v_mul_f32_e32 v99, v96, v99
	v_cvt_pk_bf16_f32 v96, v100, v101
	v_cvt_pk_bf16_f32 v97, v102, v103
	v_mul_f32_e32 v102, 0xbfb8aa3b, v92
	v_exp_f32_e32 v102, v102
	v_mul_f32_e32 v103, 0xbfb8aa3b, v93
	v_exp_f32_e32 v103, v103
	v_mad_i64_i32 v[100:101], s[22:23], v118, s48, v[112:113]
	v_lshl_add_u64 v[100:101], v[100:101], 0, v[114:115]
	v_cvt_pk_bf16_f32 v98, v104, v109
	v_cvt_pk_bf16_f32 v99, v105, v99
	global_store_dwordx4 v[100:101], v[96:99], off
	s_nop 1
	v_add_f32_e32 v96, 1.0, v102
	v_rcp_f32_e32 v96, v96
	v_add_f32_e32 v97, 1.0, v103
	v_rcp_f32_e32 v97, v97
	v_or_b32_e32 v98, 32, v150
	v_mul_f32_e32 v92, v92, v96
	v_mul_f32_e32 v84, v92, v84
	v_mul_f32_e32 v92, v93, v97
	v_mul_f32_e32 v93, 0xbfb8aa3b, v94
	v_exp_f32_e32 v93, v93
	v_mul_f32_e32 v96, 0xbfb8aa3b, v95
	v_exp_f32_e32 v96, v96
	v_mul_f32_e32 v85, v92, v85
	v_add_f32_e32 v92, 1.0, v93
	v_rcp_f32_e32 v92, v92
	v_add_f32_e32 v93, 1.0, v96
	v_mul_f32_e32 v96, 0xbfb8aa3b, v88
	v_rcp_f32_e32 v93, v93
	v_exp_f32_e32 v96, v96
	v_mul_f32_e32 v92, v94, v92
	v_mul_f32_e32 v86, v92, v86
	v_mul_f32_e32 v92, v95, v93
	v_add_f32_e32 v93, 1.0, v96
	v_rcp_f32_e32 v93, v93
	v_mul_f32_e32 v94, 0xbfb8aa3b, v89
	v_exp_f32_e32 v94, v94
	v_mul_f32_e32 v87, v92, v87
	v_mul_f32_e32 v88, v88, v93
	v_mul_f32_e32 v88, v88, v80
	v_add_f32_e32 v80, 1.0, v94
	v_mul_f32_e32 v92, 0xbfb8aa3b, v90
	v_rcp_f32_e32 v80, v80
	v_exp_f32_e32 v92, v92
	v_mul_f32_e32 v93, 0xbfb8aa3b, v91
	v_exp_f32_e32 v93, v93
	v_mul_f32_e32 v80, v89, v80
	v_add_f32_e32 v89, 1.0, v92
	v_rcp_f32_e32 v89, v89
	v_add_f32_e32 v92, 1.0, v93
	v_rcp_f32_e32 v92, v92
	v_mul_f32_e32 v93, v80, v81
	v_mul_f32_e32 v80, v90, v89
	v_mul_f32_e32 v89, v80, v82
	v_mul_f32_e32 v80, v91, v92
	v_mul_f32_e32 v83, v80, v83
	v_cvt_pk_bf16_f32 v80, v84, v85
	v_cvt_pk_bf16_f32 v81, v86, v87
	v_mul_f32_e32 v86, 0xbfb8aa3b, v76
	v_exp_f32_e32 v86, v86
	v_mul_f32_e32 v87, 0xbfb8aa3b, v77
	v_exp_f32_e32 v87, v87
	v_mad_i64_i32 v[84:85], s[22:23], v98, s48, v[112:113]
	v_lshl_add_u64 v[84:85], v[84:85], 0, v[114:115]
	v_cvt_pk_bf16_f32 v82, v88, v93
; #define PG8_BAR __builtin_amdgcn_s_barrier()
; __device__ __forceinline__ unsigned pk2(float lo, float hi) { return pg8::cvt_pk_bf16(lo, hi); }
; __device__ __forceinline__ float silu_f(float x) { return x * sigmoid_f(x); }
; template <class Epi, class Sched, bool ALIGN_EPI = false, bool SP2 = false>
; __device__ __forceinline__ void gemm_phase(PG8_LAS unsigned char* lds, const Gemm g, const Sched& S, const Epi& E) {
;     ...
;         if constexpr (!Epi::AFTER_DRAIN) { E(acc, cur, wr, wc, fr, fq); S.done(cur); }
;         if (!has_next) break;
; #pragma unroll
;         for (int a = 0; a < 2; ++a)
; #pragma unroll
;             for (int b = 0; b < 2; ++b)
; #pragma unroll
;                 for (int m = 0; m < 4; ++m)
; #pragma unroll
;                     for (int n = 0; n < 2; ++n) acc[a][b][m][n] = (f32x4){0.f, 0.f, 0.f, 0.f};
;         cur = nxt; cA = nA; cB = nB; ++ui;
;         if constexpr (ALIGN_EPI) { if (wr == 1) PG8_BAR; }
;     }
;     __device__ __forceinline__ void operator()(const f32x4 (&acc)[2][2][4][2], const pg8::Unit& u, int wr, int wc, int fr, int fq) const {
;         const int row0 = u.pm * 256 + wr * 64 + fr, col = u.pn * 128 + wc * 32 + 8 * fq;
; #pragma unroll
;         for (int ai = 0; ai < 2; ++ai)
; #pragma unroll
;             for (int m = 0; m < 4; ++m) {
;                 const int row = row0 + ai * 128 + m * 16;
;                 const float rs = sumsq ? rsqrtf(sumsq[row] * (1.f / 1024.f) + EPS) : 1.f;
;                 float o[8];
; #pragma unroll
;                 for (int n = 0; n < 2; ++n)
; #pragma unroll
;                     for (int e = 0; e < 4; ++e) { const float g = acc[ai][0][m][n][e] * rs, up = acc[ai][1][m][n][e] * rs; o[4 * n + e] = silu_f(g) * up; }
;                 u32x4 w; w.x = pk2(o[0], o[1]); w.y = pk2(o[2], o[3]); w.z = pk2(o[4], o[5]); w.w = pk2(o[6], o[7]);
;                 *(u32x4*)(H + (size_t)row * DFF + col) = w;
	v_cvt_pk_bf16_f32 v83, v89, v83
	global_store_dwordx4 v[84:85], v[80:83], off
	s_nop 1
	v_add_f32_e32 v80, 1.0, v86
	v_rcp_f32_e32 v80, v80
	v_add_f32_e32 v81, 1.0, v87
	v_rcp_f32_e32 v81, v81
	v_or_b32_e32 v82, 48, v150
	v_mul_f32_e32 v76, v76, v80
	v_mul_f32_e32 v68, v76, v68
	v_mul_f32_e32 v76, v77, v81
	v_mul_f32_e32 v77, 0xbfb8aa3b, v78
	v_exp_f32_e32 v77, v77
	v_mul_f32_e32 v80, 0xbfb8aa3b, v79
	v_exp_f32_e32 v80, v80
	v_mul_f32_e32 v69, v76, v69
	v_add_f32_e32 v76, 1.0, v77
	v_rcp_f32_e32 v76, v76
	v_add_f32_e32 v77, 1.0, v80
	v_mul_f32_e32 v80, 0xbfb8aa3b, v72
	v_rcp_f32_e32 v77, v77
	v_exp_f32_e32 v80, v80
	v_mul_f32_e32 v76, v78, v76
	v_mul_f32_e32 v70, v76, v70
	v_mul_f32_e32 v76, v79, v77
	v_add_f32_e32 v77, 1.0, v80
	v_rcp_f32_e32 v77, v77
	v_mul_f32_e32 v78, 0xbfb8aa3b, v73
	v_exp_f32_e32 v78, v78
	v_mul_f32_e32 v71, v76, v71
	v_mul_f32_e32 v72, v72, v77
	v_mul_f32_e32 v72, v72, v64
	v_add_f32_e32 v64, 1.0, v78
	v_mul_f32_e32 v76, 0xbfb8aa3b, v74
	v_rcp_f32_e32 v64, v64
	v_exp_f32_e32 v76, v76
	v_mul_f32_e32 v77, 0xbfb8aa3b, v75
	v_exp_f32_e32 v77, v77
	v_mul_f32_e32 v64, v73, v64
	v_add_f32_e32 v73, 1.0, v76
	v_rcp_f32_e32 v73, v73
	v_add_f32_e32 v76, 1.0, v77
	v_rcp_f32_e32 v76, v76
	v_mul_f32_e32 v77, v64, v65
	v_mul_f32_e32 v64, v74, v73
	v_mul_f32_e32 v73, v64, v66
	v_mul_f32_e32 v64, v75, v76
	v_mul_f32_e32 v67, v64, v67
	v_cvt_pk_bf16_f32 v64, v68, v69
	v_cvt_pk_bf16_f32 v65, v70, v71
	v_mul_f32_e32 v70, 0xbfb8aa3b, v60
	v_exp_f32_e32 v70, v70
	v_mul_f32_e32 v71, 0xbfb8aa3b, v61
	v_exp_f32_e32 v71, v71
	v_mad_i64_i32 v[68:69], s[22:23], v82, s48, v[112:113]
	v_lshl_add_u64 v[68:69], v[68:69], 0, v[114:115]
	v_cvt_pk_bf16_f32 v66, v72, v77
	v_cvt_pk_bf16_f32 v67, v73, v67
	global_store_dwordx4 v[68:69], v[64:67], off
	s_nop 1
	v_add_f32_e32 v64, 1.0, v70
	v_rcp_f32_e32 v64, v64
	v_add_f32_e32 v65, 1.0, v71
	v_rcp_f32_e32 v65, v65
	v_add_u32_e32 v66, 0x80, v150
	v_mul_f32_e32 v60, v60, v64
	v_mul_f32_e32 v52, v60, v52
	v_mul_f32_e32 v60, v61, v65
	v_mul_f32_e32 v61, 0xbfb8aa3b, v62
	v_exp_f32_e32 v61, v61
	v_mul_f32_e32 v64, 0xbfb8aa3b, v63
	v_exp_f32_e32 v64, v64
	v_mul_f32_e32 v53, v60, v53
	v_add_f32_e32 v60, 1.0, v61
	v_rcp_f32_e32 v60, v60
	v_add_f32_e32 v61, 1.0, v64
	v_mul_f32_e32 v64, 0xbfb8aa3b, v56
	v_rcp_f32_e32 v61, v61
	v_exp_f32_e32 v64, v64
	v_mul_f32_e32 v60, v62, v60
	v_mul_f32_e32 v54, v60, v54
	v_mul_f32_e32 v60, v63, v61
	v_add_f32_e32 v61, 1.0, v64
	v_rcp_f32_e32 v61, v61
	v_mul_f32_e32 v62, 0xbfb8aa3b, v57
	v_exp_f32_e32 v62, v62
	v_mul_f32_e32 v55, v60, v55
	v_mul_f32_e32 v56, v56, v61
	v_mul_f32_e32 v56, v56, v48
	v_add_f32_e32 v48, 1.0, v62
	v_mul_f32_e32 v60, 0xbfb8aa3b, v58
	v_rcp_f32_e32 v48, v48
	v_exp_f32_e32 v60, v60
	v_mul_f32_e32 v61, 0xbfb8aa3b, v59
	v_exp_f32_e32 v61, v61
	v_mul_f32_e32 v48, v57, v48
	v_add_f32_e32 v57, 1.0, v60
	v_rcp_f32_e32 v57, v57
	v_add_f32_e32 v60, 1.0, v61
	v_rcp_f32_e32 v60, v60
	v_mul_f32_e32 v61, v48, v49
	v_mul_f32_e32 v48, v58, v57
	v_mul_f32_e32 v57, v48, v50
	v_mul_f32_e32 v48, v59, v60
	v_mul_f32_e32 v51, v48, v51
	v_cvt_pk_bf16_f32 v48, v52, v53
	v_cvt_pk_bf16_f32 v49, v54, v55
	v_mul_f32_e32 v54, 0xbfb8aa3b, v44
	v_exp_f32_e32 v54, v54
	v_mul_f32_e32 v55, 0xbfb8aa3b, v45
	v_exp_f32_e32 v55, v55
	v_mad_i64_i32 v[52:53], s[22:23], v66, s48, v[112:113]
	v_lshl_add_u64 v[52:53], v[52:53], 0, v[114:115]
	v_cvt_pk_bf16_f32 v50, v56, v61
	v_cvt_pk_bf16_f32 v51, v57, v51
	global_store_dwordx4 v[52:53], v[48:51], off
	s_nop 1
	v_add_f32_e32 v48, 1.0, v54
	v_rcp_f32_e32 v48, v48
	v_add_f32_e32 v49, 1.0, v55
	v_rcp_f32_e32 v49, v49
	v_add_u32_e32 v50, 0x90, v150
	v_mul_f32_e32 v44, v44, v48
	v_mul_f32_e32 v36, v44, v36
	v_mul_f32_e32 v44, v45, v49
	v_mul_f32_e32 v45, 0xbfb8aa3b, v46
	v_exp_f32_e32 v45, v45
	v_mul_f32_e32 v48, 0xbfb8aa3b, v47
	v_exp_f32_e32 v48, v48
	v_mul_f32_e32 v37, v44, v37
	v_add_f32_e32 v44, 1.0, v45
	v_rcp_f32_e32 v44, v44
	v_add_f32_e32 v45, 1.0, v48
	v_mul_f32_e32 v48, 0xbfb8aa3b, v40
	v_rcp_f32_e32 v45, v45
	v_exp_f32_e32 v48, v48
	v_mul_f32_e32 v44, v46, v44
	v_mul_f32_e32 v38, v44, v38
	v_mul_f32_e32 v44, v47, v45
	v_add_f32_e32 v45, 1.0, v48
	v_rcp_f32_e32 v45, v45
	v_mul_f32_e32 v46, 0xbfb8aa3b, v41
	v_exp_f32_e32 v46, v46
	v_mul_f32_e32 v39, v44, v39
	v_mul_f32_e32 v40, v40, v45
	v_mul_f32_e32 v40, v40, v32
	v_add_f32_e32 v32, 1.0, v46
	v_mul_f32_e32 v44, 0xbfb8aa3b, v42
	v_rcp_f32_e32 v32, v32
	v_exp_f32_e32 v44, v44
	v_mul_f32_e32 v45, 0xbfb8aa3b, v43
	v_exp_f32_e32 v45, v45
	v_mul_f32_e32 v32, v41, v32
	v_add_f32_e32 v41, 1.0, v44
	v_rcp_f32_e32 v41, v41
	v_add_f32_e32 v44, 1.0, v45
	v_rcp_f32_e32 v44, v44
	v_mul_f32_e32 v45, v32, v33
	v_mul_f32_e32 v32, v42, v41
	v_mul_f32_e32 v41, v32, v34
	v_mul_f32_e32 v32, v43, v44
	v_mul_f32_e32 v35, v32, v35
	v_cvt_pk_bf16_f32 v32, v36, v37
	v_cvt_pk_bf16_f32 v33, v38, v39
	v_mul_f32_e32 v38, 0xbfb8aa3b, v28
	v_exp_f32_e32 v38, v38
	v_mul_f32_e32 v39, 0xbfb8aa3b, v29
	v_exp_f32_e32 v39, v39
	v_mad_i64_i32 v[36:37], s[22:23], v50, s48, v[112:113]
	v_lshl_add_u64 v[36:37], v[36:37], 0, v[114:115]
	v_cvt_pk_bf16_f32 v34, v40, v45
	v_cvt_pk_bf16_f32 v35, v41, v35
	global_store_dwordx4 v[36:37], v[32:35], off
	s_mov_b32 s98, 1
	s_cbranch_vccnz .LBB0_188
	s_andn2_b64 vcc, exec, s[2:3]
	s_cbranch_vccnz .LBB0_187
	s_barrier
	s_branch .LBB0_187
; __device__ __forceinline__ unsigned pk2(float lo, float hi) { return pg8::cvt_pk_bf16(lo, hi); }
; __device__ __forceinline__ float silu_f(float x) { return x * sigmoid_f(x); }
;     __device__ __forceinline__ void operator()(const f32x4 (&acc)[2][2][4][2], const pg8::Unit& u, int wr, int wc, int fr, int fq) const {
;         const int row0 = u.pm * 256 + wr * 64 + fr, col = u.pn * 128 + wc * 32 + 8 * fq;
; #pragma unroll
;         for (int ai = 0; ai < 2; ++ai)
; #pragma unroll
;             for (int m = 0; m < 4; ++m) {
;                 const int row = row0 + ai * 128 + m * 16;
;                 const float rs = sumsq ? rsqrtf(sumsq[row] * (1.f / 1024.f) + EPS) : 1.f;
;                 float o[8];
; #pragma unroll
;                 for (int n = 0; n < 2; ++n)
; #pragma unroll
;                     for (int e = 0; e < 4; ++e) { const float g = acc[ai][0][m][n][e] * rs, up = acc[ai][1][m][n][e] * rs; o[4 * n + e] = silu_f(g) * up; }
;                 u32x4 w; w.x = pk2(o[0], o[1]); w.y = pk2(o[2], o[3]); w.z = pk2(o[4], o[5]); w.w = pk2(o[6], o[7]);
;                 *(u32x4*)(H + (size_t)row * DFF + col) = w;
.Lp1_tail:
	s_nop 1
	v_add_f32_e32 v32, 1.0, v38
	v_rcp_f32_e32 v32, v32
	v_add_f32_e32 v33, 1.0, v39
	v_rcp_f32_e32 v33, v33
	v_add_u32_e32 v34, 0xa0, v228
	v_mul_f32_e32 v28, v28, v32
	v_mul_f32_e32 v20, v28, v20
	v_mul_f32_e32 v28, v29, v33
	v_mul_f32_e32 v29, 0xbfb8aa3b, v30
	v_exp_f32_e32 v29, v29
	v_mul_f32_e32 v32, 0xbfb8aa3b, v31
	v_exp_f32_e32 v32, v32
	v_mul_f32_e32 v21, v28, v21
	v_add_f32_e32 v28, 1.0, v29
	v_rcp_f32_e32 v28, v28
	v_add_f32_e32 v29, 1.0, v32
	v_mul_f32_e32 v32, 0xbfb8aa3b, v24
	v_rcp_f32_e32 v29, v29
	v_exp_f32_e32 v32, v32
	v_mul_f32_e32 v28, v30, v28
	v_mul_f32_e32 v22, v28, v22
	v_mul_f32_e32 v28, v31, v29
	v_add_f32_e32 v29, 1.0, v32
	v_rcp_f32_e32 v29, v29
	v_mul_f32_e32 v30, 0xbfb8aa3b, v25
	v_exp_f32_e32 v30, v30
	v_mul_f32_e32 v23, v28, v23
	v_mul_f32_e32 v24, v24, v29
	v_mul_f32_e32 v24, v24, v16
	v_add_f32_e32 v16, 1.0, v30
	v_mul_f32_e32 v28, 0xbfb8aa3b, v26
	v_rcp_f32_e32 v16, v16
	v_exp_f32_e32 v28, v28
	v_mul_f32_e32 v29, 0xbfb8aa3b, v27
	v_exp_f32_e32 v29, v29
	v_mul_f32_e32 v16, v25, v16
	v_add_f32_e32 v25, 1.0, v28
	v_rcp_f32_e32 v25, v25
	v_add_f32_e32 v28, 1.0, v29
	v_rcp_f32_e32 v28, v28
	v_mul_f32_e32 v29, v16, v17
	v_mul_f32_e32 v16, v26, v25
	v_mul_f32_e32 v25, v16, v18
	v_mul_f32_e32 v16, v27, v28
	v_mul_f32_e32 v19, v16, v19
	v_cvt_pk_bf16_f32 v16, v20, v21
	v_cvt_pk_bf16_f32 v17, v22, v23
	v_mul_f32_e32 v22, 0xbfb8aa3b, v12
	v_exp_f32_e32 v22, v22
	v_mul_f32_e32 v23, 0xbfb8aa3b, v13
	v_exp_f32_e32 v23, v23
	v_mad_i64_i32 v[20:21], s[100:101], v34, s48, v[112:113]
	v_lshl_add_u64 v[20:21], v[20:21], 0, v[114:115]
	v_cvt_pk_bf16_f32 v18, v24, v29
	v_cvt_pk_bf16_f32 v19, v25, v19
	global_store_dwordx4 v[20:21], v[16:19], off
	s_nop 1
	v_add_f32_e32 v16, 1.0, v22
	v_rcp_f32_e32 v16, v16
	v_add_f32_e32 v17, 1.0, v23
	v_rcp_f32_e32 v17, v17
	v_add_u32_e32 v18, 0xb0, v228
	v_mul_f32_e32 v12, v12, v16
	v_mul_f32_e32 v4, v12, v4
	v_mul_f32_e32 v12, v13, v17
	v_mul_f32_e32 v13, 0xbfb8aa3b, v14
	v_exp_f32_e32 v13, v13
	v_mul_f32_e32 v16, 0xbfb8aa3b, v15
	v_exp_f32_e32 v16, v16
	v_mul_f32_e32 v5, v12, v5
	v_add_f32_e32 v12, 1.0, v13
	v_rcp_f32_e32 v12, v12
	v_add_f32_e32 v13, 1.0, v16
	v_mul_f32_e32 v16, 0xbfb8aa3b, v8
	v_rcp_f32_e32 v13, v13
	v_exp_f32_e32 v16, v16
	v_mul_f32_e32 v12, v14, v12
	v_mul_f32_e32 v6, v12, v6
	v_mul_f32_e32 v12, v15, v13
	v_add_f32_e32 v13, 1.0, v16
	v_rcp_f32_e32 v13, v13
	v_mul_f32_e32 v14, 0xbfb8aa3b, v9
	v_exp_f32_e32 v14, v14
	v_mul_f32_e32 v7, v12, v7
	v_mul_f32_e32 v8, v8, v13
	v_mul_f32_e32 v8, v8, v0
	v_add_f32_e32 v0, 1.0, v14
	v_mul_f32_e32 v12, 0xbfb8aa3b, v10
	v_rcp_f32_e32 v0, v0
	v_exp_f32_e32 v12, v12
	v_mul_f32_e32 v13, 0xbfb8aa3b, v11
	v_exp_f32_e32 v13, v13
	v_mul_f32_e32 v0, v9, v0
	v_add_f32_e32 v9, 1.0, v12
	v_rcp_f32_e32 v9, v9
	v_add_f32_e32 v12, 1.0, v13
	v_rcp_f32_e32 v12, v12
	v_mul_f32_e32 v13, v0, v1
	v_mul_f32_e32 v0, v10, v9
	v_mul_f32_e32 v9, v0, v2
	v_mul_f32_e32 v0, v11, v12
	v_mul_f32_e32 v3, v0, v3
	v_cvt_pk_bf16_f32 v0, v4, v5
	v_mad_i64_i32 v[4:5], s[100:101], v18, s48, v[112:113]
	v_lshl_add_u64 v[4:5], v[4:5], 0, v[114:115]
	v_cvt_pk_bf16_f32 v1, v6, v7
	v_cvt_pk_bf16_f32 v2, v8, v13
	v_cvt_pk_bf16_f32 v3, v9, v3
	global_store_dwordx4 v[4:5], v[0:3], off
